# GEMM K-loops: block-ending barrier issued six MFMAs early; next block raises priority after its sixth MFMA
# speedup vs baseline: 1.0182x; 1.0182x over previous
; #define PG8_STAGE(bufoff, gbase, voff) do { _Pragma("unroll") for (int _i = 0; _i < 2; ++_i) \
;         __builtin_amdgcn_global_load_lds((const unsigned*)((const char*)(gbase) + (voff)[_i]), (PG8_LAS unsigned*)(lds + (bufoff) + ldsw + _i * 8192), 16, 0, 0); } while (0)
; #define PG8_LDA(dst, b, h) do { _Pragma("unroll") for (int m = 0; m < 4; ++m) _Pragma("unroll") for (int k = 0; k < 2; ++k) dst[m][k] = *(const PG8_LAS bf16x8*)(lds + PG8_SA(b, h) + aoff + m * 2048 + k * 1024); } while (0)
; #define PG8_LDB(dst, b, h) do { _Pragma("unroll") for (int n = 0; n < 2; ++n) _Pragma("unroll") for (int k = 0; k < 2; ++k) dst[n][k] = *(const PG8_LAS bf16x8*)(lds + PG8_SB(b, h) + boff + n * 2048 + k * 1024); } while (0)
; #define PG8_MMA(ai, bj, At, Bt) do { __builtin_amdgcn_s_setprio(1); _Pragma("unroll") for (int m = 0; m < 4; ++m) _Pragma("unroll") for (int n = 0; n < 2; ++n) _Pragma("unroll") for (int k = 0; k < 2; ++k) \
;         acc[ai][bj][m][n] = __builtin_amdgcn_mfma_f32_16x16x32_bf16(Bt[n][k], At[m][k], acc[ai][bj][m][n], 0, 0, 0); __builtin_amdgcn_s_setprio(0); } while (0)
; #define PG8_WAIT_V(n) asm volatile("s_waitcnt vmcnt(" #n ")" ::: "memory")
; #define PG8_BAR __builtin_amdgcn_s_barrier()
; template <class Epi, class Sched, bool ALIGN_EPI = false, bool SP2 = false>
; __device__ __forceinline__ void gemm_phase(PG8_LAS unsigned char* lds, const Gemm g, const Sched& S, const Epi& E) {
;     ...
;         for (int t = 0; t < nt; t += 2) {
;             const bool last = (t == nt - 2);
;             const char* a1 = cA + (size_t)(t + 1) * kstep;
;             const char* a2 = last ? nA : cA + (size_t)(t + 2) * kstep; const char* b2 = last ? nB : cB + (size_t)(t + 2) * kstep;
;             const char* a3 = a2 + kstep; const char* b3 = b2 + kstep;
;             if (last && has_next) S.a_ready(nxt);
;             if constexpr (SP2) {
;             PG8_LDB(B0, 0, 0); PG8_LDB(B1, 0, 1); PG8_SCHED; PG8_LDA(At, 0, 0); PG8_STAGE(PG8_SA(1, 1), a1 + hstep, voffA);
;             PG8_WAIT_V(8); PG8_WAIT_L(0); PG8_BAR; PG8_MMA(0, 0, At, B0); PG8_MMA(0, 1, At, B1); PG8_BAR; PG8_SCHED;
;             PG8_LDA(At, 0, 1); PG8_STAGE(PG8_SB(0, 0), b2, voffB); PG8_STAGE(PG8_SB(0, 1), b2 + hstep, voffB); PG8_STAGE(PG8_SA(0, 0), a2, voffA);
;             PG8_WAIT_V(8); PG8_WAIT_L(0); PG8_BAR; PG8_MMA(1, 0, At, B0); PG8_MMA(1, 1, At, B1); PG8_BAR; PG8_SCHED;
.LBB0_165:
	s_add_u32 s16, s8, 0xfffc0080
	s_addc_u32 s17, s9, -1
	s_add_i32 s18, 0, 0x10000
	s_cmp_eq_u32 s55, 12
	s_cselect_b32 s43, s14, s17
	s_cselect_b32 s42, s15, s16
	v_add_u32_e32 v0, s18, v194
	s_cselect_b32 s41, s13, s54
	s_cselect_b32 s40, s25, s53
	s_add_i32 s19, 0, 0x14000
	ds_read_b128 v[136:139], v0
	ds_read_b128 v[140:143], v0 offset:1024
	ds_read_b128 v[144:147], v0 offset:2048
	ds_read_b128 v[148:151], v0 offset:3072
	v_add_u32_e32 v0, s19, v194
	ds_read_b128 v[152:155], v0
	ds_read_b128 v[186:189], v0 offset:1024
	ds_read_b128 v[190:193], v0 offset:2048
	ds_read_b128 v[198:201], v0 offset:3072
	v_lshl_add_u64 v[2:3], s[8:9], 0, v[182:183]
	s_add_i32 m0, s45, 0xc000
	ds_read_b128 v[210:213], v196
	ds_read_b128 v[214:217], v196 offset:1024
	ds_read_b128 v[218:221], v196 offset:2048
	ds_read_b128 v[222:225], v196 offset:3072
	ds_read_b128 v[226:229], v196 offset:4096
	ds_read_b128 v[230:233], v196 offset:5120
	ds_read_b128 v[234:237], v196 offset:6144
	ds_read_b128 v[238:241], v196 offset:7168
	global_load_lds_dwordx4 v[2:3], off
	v_lshl_add_u64 v[2:3], s[8:9], 0, v[184:185]
	s_add_i32 m0, s45, 0xe000
	s_nop 0
	global_load_lds_dwordx4 v[2:3], off
	s_waitcnt vmcnt(8)
	s_waitcnt lgkmcnt(0)
	s_barrier
	s_waitcnt lgkmcnt(0)
	v_mfma_f32_16x16x32_bf16 v[132:135], v[136:139], v[210:213], v[132:135]
	v_mfma_f32_16x16x32_bf16 v[128:131], v[144:147], v[210:213], v[128:131]
	v_mfma_f32_16x16x32_bf16 v[124:127], v[136:139], v[218:221], v[124:127]
	v_mfma_f32_16x16x32_bf16 v[120:123], v[144:147], v[218:221], v[120:123]
	v_mfma_f32_16x16x32_bf16 v[116:119], v[136:139], v[226:229], v[116:119]
	v_mfma_f32_16x16x32_bf16 v[112:115], v[144:147], v[226:229], v[112:115]
	s_setprio 1
	v_mfma_f32_16x16x32_bf16 v[108:111], v[136:139], v[234:237], v[108:111]
	v_mfma_f32_16x16x32_bf16 v[104:107], v[144:147], v[234:237], v[104:107]
	v_mfma_f32_16x16x32_bf16 v[132:135], v[140:143], v[214:217], v[132:135]
	v_mfma_f32_16x16x32_bf16 v[128:131], v[148:151], v[214:217], v[128:131]
	v_mfma_f32_16x16x32_bf16 v[124:127], v[140:143], v[222:225], v[124:127]
	v_mfma_f32_16x16x32_bf16 v[120:123], v[148:151], v[222:225], v[120:123]
	v_mfma_f32_16x16x32_bf16 v[116:119], v[140:143], v[230:233], v[116:119]
	v_mfma_f32_16x16x32_bf16 v[112:115], v[148:151], v[230:233], v[112:115]
	v_mfma_f32_16x16x32_bf16 v[108:111], v[140:143], v[238:241], v[108:111]
	v_mfma_f32_16x16x32_bf16 v[104:107], v[148:151], v[238:241], v[104:107]
	s_setprio 0
	s_setprio 1
	v_mfma_f32_16x16x32_bf16 v[84:87], v[152:155], v[210:213], v[84:87]
	v_mfma_f32_16x16x32_bf16 v[76:79], v[190:193], v[210:213], v[76:79]
	v_mfma_f32_16x16x32_bf16 v[68:71], v[152:155], v[218:221], v[68:71]
	v_mfma_f32_16x16x32_bf16 v[64:67], v[190:193], v[218:221], v[64:67]
	v_mfma_f32_16x16x32_bf16 v[52:55], v[152:155], v[226:229], v[52:55]
	v_mfma_f32_16x16x32_bf16 v[48:51], v[190:193], v[226:229], v[48:51]
	v_mfma_f32_16x16x32_bf16 v[44:47], v[152:155], v[234:237], v[44:47]
	v_mfma_f32_16x16x32_bf16 v[40:43], v[190:193], v[234:237], v[40:43]
	v_mfma_f32_16x16x32_bf16 v[84:87], v[186:189], v[214:217], v[84:87]
	v_mfma_f32_16x16x32_bf16 v[76:79], v[198:201], v[214:217], v[76:79]
	s_barrier
	v_mfma_f32_16x16x32_bf16 v[68:71], v[186:189], v[222:225], v[68:71]
	v_mfma_f32_16x16x32_bf16 v[64:67], v[198:201], v[222:225], v[64:67]
	v_mfma_f32_16x16x32_bf16 v[52:55], v[186:189], v[230:233], v[52:55]
	v_mfma_f32_16x16x32_bf16 v[48:51], v[198:201], v[230:233], v[48:51]
	v_mfma_f32_16x16x32_bf16 v[44:47], v[186:189], v[238:241], v[44:47]
	v_mfma_f32_16x16x32_bf16 v[40:43], v[198:201], v[238:241], v[40:43]
	s_setprio 0
	s_add_i32 s16, s18, s44
	v_lshl_add_u64 v[2:3], s[40:41], 0, v[162:163]
	s_mov_b32 m0, s16
	ds_read_b128 v[210:213], v196 offset:16384
	ds_read_b128 v[214:217], v196 offset:17408
	ds_read_b128 v[218:221], v196 offset:18432
	ds_read_b128 v[222:225], v196 offset:19456
	ds_read_b128 v[226:229], v196 offset:20480
	ds_read_b128 v[230:233], v196 offset:21504
	ds_read_b128 v[234:237], v196 offset:22528
	ds_read_b128 v[238:241], v196 offset:23552
	global_load_lds_dwordx4 v[2:3], off
	s_add_i32 m0, s16, 0x2000
	s_add_u32 s16, s40, 0x40000
	v_lshl_add_u64 v[156:157], s[40:41], 0, v[158:159]
	s_addc_u32 s17, s41, 0
	s_add_i32 s18, s19, s44
	global_load_lds_dwordx4 v[156:157], off
	v_lshl_add_u64 v[242:243], s[16:17], 0, v[162:163]
	s_mov_b32 m0, s18
	v_lshl_add_u64 v[244:245], s[42:43], 0, v[160:161]
	global_load_lds_dwordx4 v[242:243], off
	v_lshl_add_u64 v[242:243], s[16:17], 0, v[158:159]
	s_add_i32 m0, s18, 0x2000
	s_nop 0
	global_load_lds_dwordx4 v[242:243], off
	v_lshl_add_u64 v[242:243], s[42:43], 0, v[178:179]
	s_waitcnt vmcnt(6)
	s_waitcnt lgkmcnt(0)
	s_barrier
; #define PG8_STAGE(bufoff, gbase, voff) do { _Pragma("unroll") for (int _i = 0; _i < 2; ++_i) \
;         __builtin_amdgcn_global_load_lds((const unsigned*)((const char*)(gbase) + (voff)[_i]), (PG8_LAS unsigned*)(lds + (bufoff) + ldsw + _i * 8192), 16, 0, 0); } while (0)
; #define PG8_LDA(dst, b, h) do { _Pragma("unroll") for (int m = 0; m < 4; ++m) _Pragma("unroll") for (int k = 0; k < 2; ++k) dst[m][k] = *(const PG8_LAS bf16x8*)(lds + PG8_SA(b, h) + aoff + m * 2048 + k * 1024); } while (0)
; #define PG8_LDB(dst, b, h) do { _Pragma("unroll") for (int n = 0; n < 2; ++n) _Pragma("unroll") for (int k = 0; k < 2; ++k) dst[n][k] = *(const PG8_LAS bf16x8*)(lds + PG8_SB(b, h) + boff + n * 2048 + k * 1024); } while (0)
; #define PG8_MMA(ai, bj, At, Bt) do { __builtin_amdgcn_s_setprio(1); _Pragma("unroll") for (int m = 0; m < 4; ++m) _Pragma("unroll") for (int n = 0; n < 2; ++n) _Pragma("unroll") for (int k = 0; k < 2; ++k) \
;         acc[ai][bj][m][n] = __builtin_amdgcn_mfma_f32_16x16x32_bf16(Bt[n][k], At[m][k], acc[ai][bj][m][n], 0, 0, 0); __builtin_amdgcn_s_setprio(0); } while (0)
; #define PG8_WAIT_V(n) asm volatile("s_waitcnt vmcnt(" #n ")" ::: "memory")
; #define PG8_WAIT_L(n) asm volatile("s_waitcnt lgkmcnt(" #n ")" ::: "memory")
; #define PG8_BAR __builtin_amdgcn_s_barrier()
; #define PG8_SCHED __builtin_amdgcn_sched_barrier(0)
; template <class Epi, class Sched, bool ALIGN_EPI = false, bool SP2 = false>
; __device__ __forceinline__ void gemm_phase(PG8_LAS unsigned char* lds, const Gemm g, const Sched& S, const Epi& E) {
;     ...
;             PG8_WAIT_V(8); PG8_WAIT_L(0); PG8_BAR; PG8_MMA(1, 0, At, B0); PG8_MMA(1, 1, At, B1); PG8_BAR; PG8_SCHED;
;             PG8_LDB(B0, 1, 0); PG8_LDB(B1, 1, 1); PG8_SCHED; PG8_LDA(At, 1, 0); PG8_STAGE(PG8_SA(0, 1), a2 + hstep, voffA);
;             PG8_WAIT_V(8); PG8_WAIT_L(0); PG8_BAR; PG8_MMA(0, 0, At, B0); PG8_MMA(0, 1, At, B1); PG8_BAR; PG8_SCHED;
	s_waitcnt lgkmcnt(0)
	v_mfma_f32_16x16x32_bf16 v[100:103], v[136:139], v[210:213], v[100:103]
	v_mfma_f32_16x16x32_bf16 v[96:99], v[144:147], v[210:213], v[96:99]
	v_mfma_f32_16x16x32_bf16 v[92:95], v[136:139], v[218:221], v[92:95]
	s_mov_b32 m0, s45
	v_mfma_f32_16x16x32_bf16 v[88:91], v[144:147], v[218:221], v[88:91]
	global_load_lds_dwordx4 v[242:243], off
	v_mfma_f32_16x16x32_bf16 v[80:83], v[136:139], v[226:229], v[80:83]
	v_mfma_f32_16x16x32_bf16 v[72:75], v[144:147], v[226:229], v[72:75]
	s_setprio 1
	v_mfma_f32_16x16x32_bf16 v[60:63], v[136:139], v[234:237], v[60:63]
	v_mfma_f32_16x16x32_bf16 v[56:59], v[144:147], v[234:237], v[56:59]
	v_mfma_f32_16x16x32_bf16 v[100:103], v[140:143], v[214:217], v[100:103]
	v_mfma_f32_16x16x32_bf16 v[96:99], v[148:151], v[214:217], v[96:99]
	v_mfma_f32_16x16x32_bf16 v[92:95], v[140:143], v[222:225], v[92:95]
	s_mov_b32 m0, s46
	v_mfma_f32_16x16x32_bf16 v[88:91], v[148:151], v[222:225], v[88:91]
	global_load_lds_dwordx4 v[244:245], off
	v_mfma_f32_16x16x32_bf16 v[80:83], v[140:143], v[230:233], v[80:83]
	v_mfma_f32_16x16x32_bf16 v[72:75], v[148:151], v[230:233], v[72:75]
	v_mfma_f32_16x16x32_bf16 v[60:63], v[140:143], v[238:241], v[60:63]
	v_mfma_f32_16x16x32_bf16 v[56:59], v[148:151], v[238:241], v[56:59]
	s_setprio 0
	s_setprio 1
	v_mfma_f32_16x16x32_bf16 v[36:39], v[152:155], v[210:213], v[36:39]
	v_mfma_f32_16x16x32_bf16 v[32:35], v[190:193], v[210:213], v[32:35]
	v_mfma_f32_16x16x32_bf16 v[28:31], v[152:155], v[218:221], v[28:31]
	v_mfma_f32_16x16x32_bf16 v[24:27], v[190:193], v[218:221], v[24:27]
	v_mfma_f32_16x16x32_bf16 v[20:23], v[152:155], v[226:229], v[20:23]
	v_mfma_f32_16x16x32_bf16 v[16:19], v[190:193], v[226:229], v[16:19]
	v_mfma_f32_16x16x32_bf16 v[12:15], v[152:155], v[234:237], v[12:15]
	v_mfma_f32_16x16x32_bf16 v[8:11], v[190:193], v[234:237], v[8:11]
	v_mfma_f32_16x16x32_bf16 v[36:39], v[186:189], v[214:217], v[36:39]
	v_mfma_f32_16x16x32_bf16 v[32:35], v[198:201], v[214:217], v[32:35]
	s_barrier
	v_mfma_f32_16x16x32_bf16 v[28:31], v[186:189], v[222:225], v[28:31]
	v_mfma_f32_16x16x32_bf16 v[24:27], v[198:201], v[222:225], v[24:27]
	v_mfma_f32_16x16x32_bf16 v[20:23], v[186:189], v[230:233], v[20:23]
	v_mfma_f32_16x16x32_bf16 v[16:19], v[198:201], v[230:233], v[16:19]
	v_mfma_f32_16x16x32_bf16 v[12:15], v[186:189], v[238:241], v[12:15]
	v_mfma_f32_16x16x32_bf16 v[8:11], v[198:201], v[238:241], v[8:11]
	s_setprio 0
	s_add_i32 s18, 0, 0x18000
	v_add_u32_e32 v0, s18, v194
	ds_read_b128 v[136:139], v0
	ds_read_b128 v[140:143], v0 offset:1024
	ds_read_b128 v[144:147], v0 offset:2048
	ds_read_b128 v[148:151], v0 offset:3072
	v_add_u32_e32 v0, s33, v194
	ds_read_b128 v[152:155], v0
	ds_read_b128 v[186:189], v0 offset:1024
	ds_read_b128 v[190:193], v0 offset:2048
	ds_read_b128 v[198:201], v0 offset:3072
	s_add_u32 s16, s42, 0x40000
	s_addc_u32 s17, s43, 0
	s_mov_b32 m0, s47
	v_lshl_add_u64 v[246:247], s[16:17], 0, v[178:179]
	ds_read_b128 v[210:213], v196 offset:32768
	ds_read_b128 v[214:217], v196 offset:33792
	ds_read_b128 v[218:221], v196 offset:34816
	ds_read_b128 v[222:225], v196 offset:35840
	ds_read_b128 v[226:229], v196 offset:36864
	ds_read_b128 v[230:233], v196 offset:37888
	ds_read_b128 v[234:237], v196 offset:38912
	ds_read_b128 v[238:241], v196 offset:39936
	global_load_lds_dwordx4 v[246:247], off
	v_lshl_add_u64 v[246:247], s[16:17], 0, v[160:161]
	s_mov_b32 m0, s48
	s_nop 0
	global_load_lds_dwordx4 v[246:247], off
	s_waitcnt vmcnt(8)
	s_waitcnt lgkmcnt(0)
	s_barrier
	s_waitcnt lgkmcnt(0)
	v_mfma_f32_16x16x32_bf16 v[132:135], v[136:139], v[210:213], v[132:135]
	v_mfma_f32_16x16x32_bf16 v[128:131], v[144:147], v[210:213], v[128:131]
	v_mfma_f32_16x16x32_bf16 v[124:127], v[136:139], v[218:221], v[124:127]
	v_mfma_f32_16x16x32_bf16 v[120:123], v[144:147], v[218:221], v[120:123]
	v_mfma_f32_16x16x32_bf16 v[116:119], v[136:139], v[226:229], v[116:119]
	v_mfma_f32_16x16x32_bf16 v[112:115], v[144:147], v[226:229], v[112:115]
	s_setprio 1
	v_mfma_f32_16x16x32_bf16 v[108:111], v[136:139], v[234:237], v[108:111]
	v_mfma_f32_16x16x32_bf16 v[104:107], v[144:147], v[234:237], v[104:107]
	v_mfma_f32_16x16x32_bf16 v[132:135], v[140:143], v[214:217], v[132:135]
	v_mfma_f32_16x16x32_bf16 v[128:131], v[148:151], v[214:217], v[128:131]
	v_mfma_f32_16x16x32_bf16 v[124:127], v[140:143], v[222:225], v[124:127]
	v_mfma_f32_16x16x32_bf16 v[120:123], v[148:151], v[222:225], v[120:123]
	v_mfma_f32_16x16x32_bf16 v[116:119], v[140:143], v[230:233], v[116:119]
	v_mfma_f32_16x16x32_bf16 v[112:115], v[148:151], v[230:233], v[112:115]
	v_mfma_f32_16x16x32_bf16 v[108:111], v[140:143], v[238:241], v[108:111]
	v_mfma_f32_16x16x32_bf16 v[104:107], v[148:151], v[238:241], v[104:107]
	s_setprio 0
	s_setprio 1
	v_mfma_f32_16x16x32_bf16 v[84:87], v[152:155], v[210:213], v[84:87]
	v_mfma_f32_16x16x32_bf16 v[76:79], v[190:193], v[210:213], v[76:79]
	v_mfma_f32_16x16x32_bf16 v[68:71], v[152:155], v[218:221], v[68:71]
	v_mfma_f32_16x16x32_bf16 v[64:67], v[190:193], v[218:221], v[64:67]
	v_mfma_f32_16x16x32_bf16 v[52:55], v[152:155], v[226:229], v[52:55]
	v_mfma_f32_16x16x32_bf16 v[48:51], v[190:193], v[226:229], v[48:51]
	v_mfma_f32_16x16x32_bf16 v[44:47], v[152:155], v[234:237], v[44:47]
	v_mfma_f32_16x16x32_bf16 v[40:43], v[190:193], v[234:237], v[40:43]
	v_mfma_f32_16x16x32_bf16 v[84:87], v[186:189], v[214:217], v[84:87]
	v_mfma_f32_16x16x32_bf16 v[76:79], v[198:201], v[214:217], v[76:79]
	s_barrier
; #define PG8_STAGE(bufoff, gbase, voff) do { _Pragma("unroll") for (int _i = 0; _i < 2; ++_i) \
;         __builtin_amdgcn_global_load_lds((const unsigned*)((const char*)(gbase) + (voff)[_i]), (PG8_LAS unsigned*)(lds + (bufoff) + ldsw + _i * 8192), 16, 0, 0); } while (0)
; #define PG8_LDA(dst, b, h) do { _Pragma("unroll") for (int m = 0; m < 4; ++m) _Pragma("unroll") for (int k = 0; k < 2; ++k) dst[m][k] = *(const PG8_LAS bf16x8*)(lds + PG8_SA(b, h) + aoff + m * 2048 + k * 1024); } while (0)
; #define PG8_MMA(ai, bj, At, Bt) do { __builtin_amdgcn_s_setprio(1); _Pragma("unroll") for (int m = 0; m < 4; ++m) _Pragma("unroll") for (int n = 0; n < 2; ++n) _Pragma("unroll") for (int k = 0; k < 2; ++k) \
;         acc[ai][bj][m][n] = __builtin_amdgcn_mfma_f32_16x16x32_bf16(Bt[n][k], At[m][k], acc[ai][bj][m][n], 0, 0, 0); __builtin_amdgcn_s_setprio(0); } while (0)
; #define PG8_WAIT_V(n) asm volatile("s_waitcnt vmcnt(" #n ")" ::: "memory")
; #define PG8_WAIT_L(n) asm volatile("s_waitcnt lgkmcnt(" #n ")" ::: "memory")
; #define PG8_BAR __builtin_amdgcn_s_barrier()
; #define PG8_SCHED __builtin_amdgcn_sched_barrier(0)
; template <class Epi, class Sched, bool ALIGN_EPI = false, bool SP2 = false>
; __device__ __forceinline__ void gemm_phase(PG8_LAS unsigned char* lds, const Gemm g, const Sched& S, const Epi& E) {
;     ...
;             PG8_WAIT_V(8); PG8_WAIT_L(0); PG8_BAR; PG8_MMA(0, 0, At, B0); PG8_MMA(0, 1, At, B1); PG8_BAR; PG8_SCHED;
;             PG8_LDA(At, 1, 1); PG8_STAGE(PG8_SB(1, 0), b3, voffB); PG8_STAGE(PG8_SB(1, 1), b3 + hstep, voffB); PG8_STAGE(PG8_SA(1, 0), a3, voffA);
;             PG8_WAIT_V(8); PG8_WAIT_L(0); PG8_BAR; PG8_MMA(1, 0, At, B0); PG8_MMA(1, 1, At, B1); PG8_BAR; PG8_SCHED;
	v_mfma_f32_16x16x32_bf16 v[68:71], v[186:189], v[222:225], v[68:71]
	v_mfma_f32_16x16x32_bf16 v[64:67], v[198:201], v[222:225], v[64:67]
	v_mfma_f32_16x16x32_bf16 v[52:55], v[186:189], v[230:233], v[52:55]
	v_mfma_f32_16x16x32_bf16 v[48:51], v[198:201], v[230:233], v[48:51]
	v_mfma_f32_16x16x32_bf16 v[44:47], v[186:189], v[238:241], v[44:47]
	v_mfma_f32_16x16x32_bf16 v[40:43], v[198:201], v[238:241], v[40:43]
	s_setprio 0
	s_add_i32 s16, s18, s44
	v_lshl_add_u64 v[2:3], v[2:3], 0, s[20:21]
	s_mov_b32 m0, s16
	ds_read_b128 v[210:213], v196 offset:49152
	ds_read_b128 v[214:217], v196 offset:50176
	ds_read_b128 v[218:221], v196 offset:51200
	ds_read_b128 v[222:225], v196 offset:52224
	ds_read_b128 v[226:229], v196 offset:53248
	ds_read_b128 v[230:233], v196 offset:54272
	ds_read_b128 v[234:237], v196 offset:55296
	ds_read_b128 v[238:241], v196 offset:56320
	global_load_lds_dwordx4 v[2:3], off
	s_add_i32 m0, s16, 0x2000
	s_add_u32 s16, s40, 0x40080
	v_lshl_add_u64 v[2:3], v[156:157], 0, s[20:21]
	s_addc_u32 s17, s41, 0
	s_add_i32 s18, s33, s44
	global_load_lds_dwordx4 v[2:3], off
	v_lshl_add_u64 v[2:3], s[16:17], 0, v[162:163]
	s_mov_b32 m0, s18
	s_nop 0
	global_load_lds_dwordx4 v[2:3], off
	v_lshl_add_u64 v[2:3], s[16:17], 0, v[158:159]
	s_add_i32 m0, s18, 0x2000
	s_nop 0
	global_load_lds_dwordx4 v[2:3], off
	v_lshl_add_u64 v[2:3], v[242:243], 0, s[20:21]
	v_lshl_add_u64 v[244:245], v[244:245], 0, s[20:21]
	s_waitcnt vmcnt(6)
	s_waitcnt lgkmcnt(0)
	s_barrier
	s_waitcnt lgkmcnt(0)
	v_mfma_f32_16x16x32_bf16 v[100:103], v[136:139], v[210:213], v[100:103]
	v_mfma_f32_16x16x32_bf16 v[96:99], v[144:147], v[210:213], v[96:99]
	v_mfma_f32_16x16x32_bf16 v[92:95], v[136:139], v[218:221], v[92:95]
	s_mov_b32 m0, s49
	v_mfma_f32_16x16x32_bf16 v[88:91], v[144:147], v[218:221], v[88:91]
	global_load_lds_dwordx4 v[2:3], off
	v_mfma_f32_16x16x32_bf16 v[80:83], v[136:139], v[226:229], v[80:83]
	v_mfma_f32_16x16x32_bf16 v[72:75], v[144:147], v[226:229], v[72:75]
	s_setprio 1
	v_mfma_f32_16x16x32_bf16 v[60:63], v[136:139], v[234:237], v[60:63]
	v_mfma_f32_16x16x32_bf16 v[56:59], v[144:147], v[234:237], v[56:59]
	v_mfma_f32_16x16x32_bf16 v[100:103], v[140:143], v[214:217], v[100:103]
	v_mfma_f32_16x16x32_bf16 v[96:99], v[148:151], v[214:217], v[96:99]
	v_mfma_f32_16x16x32_bf16 v[92:95], v[140:143], v[222:225], v[92:95]
	s_mov_b32 m0, s50
	v_mfma_f32_16x16x32_bf16 v[88:91], v[148:151], v[222:225], v[88:91]
	global_load_lds_dwordx4 v[244:245], off
	v_mfma_f32_16x16x32_bf16 v[80:83], v[140:143], v[230:233], v[80:83]
	v_mfma_f32_16x16x32_bf16 v[72:75], v[148:151], v[230:233], v[72:75]
	v_mfma_f32_16x16x32_bf16 v[60:63], v[140:143], v[238:241], v[60:63]
	v_mfma_f32_16x16x32_bf16 v[56:59], v[148:151], v[238:241], v[56:59]
	s_setprio 0
	s_setprio 1
	v_mfma_f32_16x16x32_bf16 v[36:39], v[152:155], v[210:213], v[36:39]
	v_mfma_f32_16x16x32_bf16 v[32:35], v[190:193], v[210:213], v[32:35]
	v_mfma_f32_16x16x32_bf16 v[28:31], v[152:155], v[218:221], v[28:31]
	v_mfma_f32_16x16x32_bf16 v[24:27], v[190:193], v[218:221], v[24:27]
	v_mfma_f32_16x16x32_bf16 v[20:23], v[152:155], v[226:229], v[20:23]
	v_mfma_f32_16x16x32_bf16 v[16:19], v[190:193], v[226:229], v[16:19]
	v_mfma_f32_16x16x32_bf16 v[12:15], v[152:155], v[234:237], v[12:15]
	v_mfma_f32_16x16x32_bf16 v[8:11], v[190:193], v[234:237], v[8:11]
	v_mfma_f32_16x16x32_bf16 v[36:39], v[186:189], v[214:217], v[36:39]
	v_mfma_f32_16x16x32_bf16 v[32:35], v[198:201], v[214:217], v[32:35]
	s_barrier
	v_mfma_f32_16x16x32_bf16 v[28:31], v[186:189], v[222:225], v[28:31]
	v_mfma_f32_16x16x32_bf16 v[24:27], v[198:201], v[222:225], v[24:27]
	v_mfma_f32_16x16x32_bf16 v[20:23], v[186:189], v[230:233], v[20:23]
	v_mfma_f32_16x16x32_bf16 v[16:19], v[198:201], v[230:233], v[16:19]
	v_mfma_f32_16x16x32_bf16 v[12:15], v[186:189], v[238:241], v[12:15]
	v_mfma_f32_16x16x32_bf16 v[8:11], v[198:201], v[238:241], v[8:11]
	s_setprio 0
	s_add_i32 s55, s55, 2
	s_add_u32 s8, s8, 0x100
	s_addc_u32 s9, s9, 0
	s_add_u32 s53, s53, 0x100
	s_addc_u32 s54, s54, 0
	s_cmp_gt_u32 s55, 13
	s_cbranch_scc0 .LBB0_165
	s_and_b64 vcc, exec, s[10:11]
	s_cbranch_vccz .LBB0_168
	s_barrier
	s_setprio 1

; #define PG8_STAGE(bufoff, gbase, voff) do { _Pragma("unroll") for (int _i = 0; _i < 2; ++_i) \
;         __builtin_amdgcn_global_load_lds((const unsigned*)((const char*)(gbase) + (voff)[_i]), (PG8_LAS unsigned*)(lds + (bufoff) + ldsw + _i * 8192), 16, 0, 0); } while (0)
; #define PG8_LDA(dst, b, h) do { _Pragma("unroll") for (int m = 0; m < 4; ++m) _Pragma("unroll") for (int k = 0; k < 2; ++k) dst[m][k] = *(const PG8_LAS bf16x8*)(lds + PG8_SA(b, h) + aoff + m * 2048 + k * 1024); } while (0)
; #define PG8_LDB(dst, b, h) do { _Pragma("unroll") for (int n = 0; n < 2; ++n) _Pragma("unroll") for (int k = 0; k < 2; ++k) dst[n][k] = *(const PG8_LAS bf16x8*)(lds + PG8_SB(b, h) + boff + n * 2048 + k * 1024); } while (0)
; #define PG8_MMA(ai, bj, At, Bt) do { __builtin_amdgcn_s_setprio(1); _Pragma("unroll") for (int m = 0; m < 4; ++m) _Pragma("unroll") for (int n = 0; n < 2; ++n) _Pragma("unroll") for (int k = 0; k < 2; ++k) \
;         acc[ai][bj][m][n] = __builtin_amdgcn_mfma_f32_16x16x32_bf16(Bt[n][k], At[m][k], acc[ai][bj][m][n], 0, 0, 0); __builtin_amdgcn_s_setprio(0); } while (0)
; #define PG8_WAIT_V(n) asm volatile("s_waitcnt vmcnt(" #n ")" ::: "memory")
; #define PG8_BAR __builtin_amdgcn_s_barrier()
; template <class Epi, class Sched, bool ALIGN_EPI = false, bool SP2 = false>
; __device__ __forceinline__ void gemm_phase(PG8_LAS unsigned char* lds, const Gemm g, const Sched& S, const Epi& E) {
;     ...
;         for (int t = 0; t < nt; t += 2) {
;             const bool last = (t == nt - 2);
;             const char* a1 = cA + (size_t)(t + 1) * kstep;
;             const char* a2 = last ? nA : cA + (size_t)(t + 2) * kstep; const char* b2 = last ? nB : cB + (size_t)(t + 2) * kstep;
;             const char* a3 = a2 + kstep; const char* b3 = b2 + kstep;
;             if (last && has_next) S.a_ready(nxt);
;             if constexpr (SP2) {
;             PG8_LDB(B0, 0, 0); PG8_LDB(B1, 0, 1); PG8_SCHED; PG8_LDA(At, 0, 0); PG8_STAGE(PG8_SA(1, 1), a1 + hstep, voffA);
;             PG8_WAIT_V(8); PG8_WAIT_L(0); PG8_BAR; PG8_MMA(0, 0, At, B0); PG8_MMA(0, 1, At, B1); PG8_BAR; PG8_SCHED;
;             PG8_LDA(At, 0, 1); PG8_STAGE(PG8_SB(0, 0), b2, voffB); PG8_STAGE(PG8_SB(0, 1), b2 + hstep, voffB); PG8_STAGE(PG8_SA(0, 0), a2, voffA);
;             PG8_WAIT_V(8); PG8_WAIT_L(0); PG8_BAR; PG8_MMA(1, 0, At, B0); PG8_MMA(1, 1, At, B1); PG8_BAR; PG8_SCHED;
.LBB0_203:
	s_add_i32 s36, s28, 2
	s_add_u32 s16, s24, 0x80
	s_addc_u32 s17, s25, 0
	s_add_i32 s18, 0, 0x10000
	s_cmp_eq_u32 s60, s28
	s_cselect_b32 s29, s3, s17
	s_cselect_b32 s28, s2, s16
	v_add_u32_e32 v137, s18, v200
	s_cselect_b32 s17, s9, s35
	s_cselect_b32 s16, s8, s23
	s_add_i32 s19, 0, 0x14000
	ds_read_b128 v[144:147], v137
	ds_read_b128 v[148:151], v137 offset:1024
	ds_read_b128 v[152:155], v137 offset:2048
	ds_read_b128 v[156:159], v137 offset:3072
	v_add_u32_e32 v137, s19, v200
	ds_read_b128 v[160:163], v137
	ds_read_b128 v[178:181], v137 offset:1024
	ds_read_b128 v[182:185], v137 offset:2048
	ds_read_b128 v[186:189], v137 offset:3072
	v_lshl_add_u64 v[198:199], s[24:25], 0, v[140:141]
	s_add_i32 m0, s52, 0xc000
	ds_read_b128 v[190:193], v210
	ds_read_b128 v[194:197], v210 offset:1024
	ds_read_b128 v[212:215], v210 offset:2048
	ds_read_b128 v[216:219], v210 offset:3072
	ds_read_b128 v[220:223], v210 offset:4096
	ds_read_b128 v[224:227], v210 offset:5120
	ds_read_b128 v[228:231], v210 offset:6144
	ds_read_b128 v[232:235], v210 offset:7168
	global_load_lds_dwordx4 v[198:199], off
	v_lshl_add_u64 v[198:199], s[24:25], 0, v[142:143]
	s_add_i32 m0, s52, 0xe000
	s_nop 0
	global_load_lds_dwordx4 v[198:199], off
	s_waitcnt vmcnt(8)
	s_waitcnt lgkmcnt(0)
	s_barrier
	s_waitcnt lgkmcnt(0)
	v_mfma_f32_16x16x32_bf16 v[132:135], v[144:147], v[190:193], v[132:135]
	v_mfma_f32_16x16x32_bf16 v[128:131], v[152:155], v[190:193], v[128:131]
	v_mfma_f32_16x16x32_bf16 v[116:119], v[144:147], v[212:215], v[116:119]
	v_mfma_f32_16x16x32_bf16 v[112:115], v[152:155], v[212:215], v[112:115]
	v_mfma_f32_16x16x32_bf16 v[100:103], v[144:147], v[220:223], v[100:103]
	v_mfma_f32_16x16x32_bf16 v[96:99], v[152:155], v[220:223], v[96:99]
	s_setprio 1
	v_mfma_f32_16x16x32_bf16 v[84:87], v[144:147], v[228:231], v[84:87]
	v_mfma_f32_16x16x32_bf16 v[80:83], v[152:155], v[228:231], v[80:83]
	v_mfma_f32_16x16x32_bf16 v[132:135], v[148:151], v[194:197], v[132:135]
	v_mfma_f32_16x16x32_bf16 v[128:131], v[156:159], v[194:197], v[128:131]
	v_mfma_f32_16x16x32_bf16 v[116:119], v[148:151], v[216:219], v[116:119]
	v_mfma_f32_16x16x32_bf16 v[112:115], v[156:159], v[216:219], v[112:115]
	v_mfma_f32_16x16x32_bf16 v[100:103], v[148:151], v[224:227], v[100:103]
	v_mfma_f32_16x16x32_bf16 v[96:99], v[156:159], v[224:227], v[96:99]
	v_mfma_f32_16x16x32_bf16 v[84:87], v[148:151], v[232:235], v[84:87]
	v_mfma_f32_16x16x32_bf16 v[80:83], v[156:159], v[232:235], v[80:83]
	s_setprio 0
	s_setprio 1
	v_mfma_f32_16x16x32_bf16 v[124:127], v[160:163], v[190:193], v[124:127]
	v_mfma_f32_16x16x32_bf16 v[120:123], v[182:185], v[190:193], v[120:123]
	v_mfma_f32_16x16x32_bf16 v[108:111], v[160:163], v[212:215], v[108:111]
	v_mfma_f32_16x16x32_bf16 v[104:107], v[182:185], v[212:215], v[104:107]
	v_mfma_f32_16x16x32_bf16 v[92:95], v[160:163], v[220:223], v[92:95]
	v_mfma_f32_16x16x32_bf16 v[88:91], v[182:185], v[220:223], v[88:91]
	v_mfma_f32_16x16x32_bf16 v[76:79], v[160:163], v[228:231], v[76:79]
	v_mfma_f32_16x16x32_bf16 v[72:75], v[182:185], v[228:231], v[72:75]
	v_mfma_f32_16x16x32_bf16 v[124:127], v[178:181], v[194:197], v[124:127]
	v_mfma_f32_16x16x32_bf16 v[120:123], v[186:189], v[194:197], v[120:123]
	s_barrier
	v_mfma_f32_16x16x32_bf16 v[108:111], v[178:181], v[216:219], v[108:111]
	v_mfma_f32_16x16x32_bf16 v[104:107], v[186:189], v[216:219], v[104:107]
	v_mfma_f32_16x16x32_bf16 v[92:95], v[178:181], v[224:227], v[92:95]
	v_mfma_f32_16x16x32_bf16 v[88:91], v[186:189], v[224:227], v[88:91]
	v_mfma_f32_16x16x32_bf16 v[76:79], v[178:181], v[232:235], v[76:79]
	v_mfma_f32_16x16x32_bf16 v[72:75], v[186:189], v[232:235], v[72:75]
	s_setprio 0
	s_add_i32 s18, s18, s41
	v_lshl_add_u64 v[198:199], s[16:17], 0, v[0:1]
	s_mov_b32 m0, s18
	ds_read_b128 v[190:193], v210 offset:16384
	ds_read_b128 v[194:197], v210 offset:17408
	ds_read_b128 v[212:215], v210 offset:18432
	ds_read_b128 v[216:219], v210 offset:19456
	ds_read_b128 v[220:223], v210 offset:20480
	ds_read_b128 v[224:227], v210 offset:21504
	ds_read_b128 v[228:231], v210 offset:22528
	ds_read_b128 v[232:235], v210 offset:23552
	global_load_lds_dwordx4 v[198:199], off
	s_add_i32 m0, s18, 0x2000
	v_lshl_add_u64 v[236:237], s[16:17], 0, v[2:3]
	s_add_u32 s16, s16, s12
	s_addc_u32 s17, s17, 0
	s_add_i32 s18, s19, s41
	global_load_lds_dwordx4 v[236:237], off
	v_lshl_add_u64 v[238:239], s[16:17], 0, v[0:1]
	s_mov_b32 m0, s18
	v_lshl_add_u64 v[240:241], s[16:17], 0, v[2:3]
	global_load_lds_dwordx4 v[238:239], off
	s_add_i32 m0, s18, 0x2000
	v_lshl_add_u64 v[242:243], s[28:29], 0, v[0:1]
	global_load_lds_dwordx4 v[240:241], off
	v_lshl_add_u64 v[244:245], s[28:29], 0, v[2:3]
	s_waitcnt vmcnt(6)
	s_waitcnt lgkmcnt(0)
	s_barrier
; #define PG8_STAGE(bufoff, gbase, voff) do { _Pragma("unroll") for (int _i = 0; _i < 2; ++_i) \
;         __builtin_amdgcn_global_load_lds((const unsigned*)((const char*)(gbase) + (voff)[_i]), (PG8_LAS unsigned*)(lds + (bufoff) + ldsw + _i * 8192), 16, 0, 0); } while (0)
; #define PG8_LDA(dst, b, h) do { _Pragma("unroll") for (int m = 0; m < 4; ++m) _Pragma("unroll") for (int k = 0; k < 2; ++k) dst[m][k] = *(const PG8_LAS bf16x8*)(lds + PG8_SA(b, h) + aoff + m * 2048 + k * 1024); } while (0)
; #define PG8_LDB(dst, b, h) do { _Pragma("unroll") for (int n = 0; n < 2; ++n) _Pragma("unroll") for (int k = 0; k < 2; ++k) dst[n][k] = *(const PG8_LAS bf16x8*)(lds + PG8_SB(b, h) + boff + n * 2048 + k * 1024); } while (0)
; #define PG8_MMA(ai, bj, At, Bt) do { __builtin_amdgcn_s_setprio(1); _Pragma("unroll") for (int m = 0; m < 4; ++m) _Pragma("unroll") for (int n = 0; n < 2; ++n) _Pragma("unroll") for (int k = 0; k < 2; ++k) \
;         acc[ai][bj][m][n] = __builtin_amdgcn_mfma_f32_16x16x32_bf16(Bt[n][k], At[m][k], acc[ai][bj][m][n], 0, 0, 0); __builtin_amdgcn_s_setprio(0); } while (0)
; #define PG8_WAIT_V(n) asm volatile("s_waitcnt vmcnt(" #n ")" ::: "memory")
; #define PG8_WAIT_L(n) asm volatile("s_waitcnt lgkmcnt(" #n ")" ::: "memory")
; #define PG8_BAR __builtin_amdgcn_s_barrier()
; #define PG8_SCHED __builtin_amdgcn_sched_barrier(0)
; template <class Epi, class Sched, bool ALIGN_EPI = false, bool SP2 = false>
; __device__ __forceinline__ void gemm_phase(PG8_LAS unsigned char* lds, const Gemm g, const Sched& S, const Epi& E) {
;     ...
;             PG8_WAIT_V(8); PG8_WAIT_L(0); PG8_BAR; PG8_MMA(1, 0, At, B0); PG8_MMA(1, 1, At, B1); PG8_BAR; PG8_SCHED;
;             PG8_LDB(B0, 1, 0); PG8_LDB(B1, 1, 1); PG8_SCHED; PG8_LDA(At, 1, 0); PG8_STAGE(PG8_SA(0, 1), a2 + hstep, voffA);
;             PG8_WAIT_V(8); PG8_WAIT_L(0); PG8_BAR; PG8_MMA(0, 0, At, B0); PG8_MMA(0, 1, At, B1); PG8_BAR; PG8_SCHED;
	s_waitcnt lgkmcnt(0)
	v_mfma_f32_16x16x32_bf16 v[68:71], v[144:147], v[190:193], v[68:71]
	v_mfma_f32_16x16x32_bf16 v[64:67], v[152:155], v[190:193], v[64:67]
	v_mfma_f32_16x16x32_bf16 v[52:55], v[144:147], v[212:215], v[52:55]
	s_mov_b32 m0, s52
	v_mfma_f32_16x16x32_bf16 v[48:51], v[152:155], v[212:215], v[48:51]
	global_load_lds_dwordx4 v[242:243], off
	v_mfma_f32_16x16x32_bf16 v[36:39], v[144:147], v[220:223], v[36:39]
	v_mfma_f32_16x16x32_bf16 v[32:35], v[152:155], v[220:223], v[32:35]
	s_setprio 1
	v_mfma_f32_16x16x32_bf16 v[20:23], v[144:147], v[228:231], v[20:23]
	v_mfma_f32_16x16x32_bf16 v[16:19], v[152:155], v[228:231], v[16:19]
	v_mfma_f32_16x16x32_bf16 v[68:71], v[148:151], v[194:197], v[68:71]
	v_mfma_f32_16x16x32_bf16 v[64:67], v[156:159], v[194:197], v[64:67]
	v_mfma_f32_16x16x32_bf16 v[52:55], v[148:151], v[216:219], v[52:55]
	s_mov_b32 m0, s53
	v_mfma_f32_16x16x32_bf16 v[48:51], v[156:159], v[216:219], v[48:51]
	global_load_lds_dwordx4 v[244:245], off
	v_mfma_f32_16x16x32_bf16 v[36:39], v[148:151], v[224:227], v[36:39]
	v_mfma_f32_16x16x32_bf16 v[32:35], v[156:159], v[224:227], v[32:35]
	v_mfma_f32_16x16x32_bf16 v[20:23], v[148:151], v[232:235], v[20:23]
	v_mfma_f32_16x16x32_bf16 v[16:19], v[156:159], v[232:235], v[16:19]
	s_setprio 0
	s_setprio 1
	v_mfma_f32_16x16x32_bf16 v[60:63], v[160:163], v[190:193], v[60:63]
	v_mfma_f32_16x16x32_bf16 v[56:59], v[182:185], v[190:193], v[56:59]
	v_mfma_f32_16x16x32_bf16 v[44:47], v[160:163], v[212:215], v[44:47]
	v_mfma_f32_16x16x32_bf16 v[40:43], v[182:185], v[212:215], v[40:43]
	v_mfma_f32_16x16x32_bf16 v[28:31], v[160:163], v[220:223], v[28:31]
	v_mfma_f32_16x16x32_bf16 v[24:27], v[182:185], v[220:223], v[24:27]
	v_mfma_f32_16x16x32_bf16 v[12:15], v[160:163], v[228:231], v[12:15]
	v_mfma_f32_16x16x32_bf16 v[8:11], v[182:185], v[228:231], v[8:11]
	v_mfma_f32_16x16x32_bf16 v[60:63], v[178:181], v[194:197], v[60:63]
	v_mfma_f32_16x16x32_bf16 v[56:59], v[186:189], v[194:197], v[56:59]
	s_barrier
	v_mfma_f32_16x16x32_bf16 v[44:47], v[178:181], v[216:219], v[44:47]
	v_mfma_f32_16x16x32_bf16 v[40:43], v[186:189], v[216:219], v[40:43]
	v_mfma_f32_16x16x32_bf16 v[28:31], v[178:181], v[224:227], v[28:31]
	v_mfma_f32_16x16x32_bf16 v[24:27], v[186:189], v[224:227], v[24:27]
	v_mfma_f32_16x16x32_bf16 v[12:15], v[178:181], v[232:235], v[12:15]
	v_mfma_f32_16x16x32_bf16 v[8:11], v[186:189], v[232:235], v[8:11]
	s_setprio 0
	s_add_i32 s18, 0, 0x18000
	v_add_u32_e32 v137, s18, v200
	ds_read_b128 v[144:147], v137
	ds_read_b128 v[148:151], v137 offset:1024
	ds_read_b128 v[152:155], v137 offset:2048
	ds_read_b128 v[156:159], v137 offset:3072
	v_add_u32_e32 v137, s33, v200
	ds_read_b128 v[160:163], v137
	ds_read_b128 v[178:181], v137 offset:1024
	ds_read_b128 v[182:185], v137 offset:2048
	ds_read_b128 v[186:189], v137 offset:3072
	s_add_u32 s16, s28, s12
	s_addc_u32 s17, s29, 0
	s_mov_b32 m0, s54
	v_lshl_add_u64 v[246:247], s[16:17], 0, v[0:1]
	ds_read_b128 v[190:193], v210 offset:32768
	ds_read_b128 v[194:197], v210 offset:33792
	ds_read_b128 v[212:215], v210 offset:34816
	ds_read_b128 v[216:219], v210 offset:35840
	ds_read_b128 v[220:223], v210 offset:36864
	ds_read_b128 v[224:227], v210 offset:37888
	ds_read_b128 v[228:231], v210 offset:38912
	ds_read_b128 v[232:235], v210 offset:39936
	global_load_lds_dwordx4 v[246:247], off
	v_lshl_add_u64 v[246:247], s[16:17], 0, v[2:3]
	s_mov_b32 m0, s55
	s_nop 0
	global_load_lds_dwordx4 v[246:247], off
	s_waitcnt vmcnt(8)
	s_waitcnt lgkmcnt(0)
	s_barrier
	s_waitcnt lgkmcnt(0)
	v_mfma_f32_16x16x32_bf16 v[132:135], v[144:147], v[190:193], v[132:135]
	v_mfma_f32_16x16x32_bf16 v[128:131], v[152:155], v[190:193], v[128:131]
	v_mfma_f32_16x16x32_bf16 v[116:119], v[144:147], v[212:215], v[116:119]
	v_mfma_f32_16x16x32_bf16 v[112:115], v[152:155], v[212:215], v[112:115]
	v_mfma_f32_16x16x32_bf16 v[100:103], v[144:147], v[220:223], v[100:103]
	v_mfma_f32_16x16x32_bf16 v[96:99], v[152:155], v[220:223], v[96:99]
	s_setprio 1
	v_mfma_f32_16x16x32_bf16 v[84:87], v[144:147], v[228:231], v[84:87]
	v_mfma_f32_16x16x32_bf16 v[80:83], v[152:155], v[228:231], v[80:83]
	v_mfma_f32_16x16x32_bf16 v[132:135], v[148:151], v[194:197], v[132:135]
	v_mfma_f32_16x16x32_bf16 v[128:131], v[156:159], v[194:197], v[128:131]
	v_mfma_f32_16x16x32_bf16 v[116:119], v[148:151], v[216:219], v[116:119]
	v_mfma_f32_16x16x32_bf16 v[112:115], v[156:159], v[216:219], v[112:115]
	v_mfma_f32_16x16x32_bf16 v[100:103], v[148:151], v[224:227], v[100:103]
	v_mfma_f32_16x16x32_bf16 v[96:99], v[156:159], v[224:227], v[96:99]
	v_mfma_f32_16x16x32_bf16 v[84:87], v[148:151], v[232:235], v[84:87]
	v_mfma_f32_16x16x32_bf16 v[80:83], v[156:159], v[232:235], v[80:83]
	s_setprio 0
	s_setprio 1
	v_mfma_f32_16x16x32_bf16 v[124:127], v[160:163], v[190:193], v[124:127]
	v_mfma_f32_16x16x32_bf16 v[120:123], v[182:185], v[190:193], v[120:123]
	v_mfma_f32_16x16x32_bf16 v[108:111], v[160:163], v[212:215], v[108:111]
	v_mfma_f32_16x16x32_bf16 v[104:107], v[182:185], v[212:215], v[104:107]
	v_mfma_f32_16x16x32_bf16 v[92:95], v[160:163], v[220:223], v[92:95]
	v_mfma_f32_16x16x32_bf16 v[88:91], v[182:185], v[220:223], v[88:91]
	v_mfma_f32_16x16x32_bf16 v[76:79], v[160:163], v[228:231], v[76:79]
	v_mfma_f32_16x16x32_bf16 v[72:75], v[182:185], v[228:231], v[72:75]
	v_mfma_f32_16x16x32_bf16 v[124:127], v[178:181], v[194:197], v[124:127]
	v_mfma_f32_16x16x32_bf16 v[120:123], v[186:189], v[194:197], v[120:123]
	s_barrier
; #define PG8_STAGE(bufoff, gbase, voff) do { _Pragma("unroll") for (int _i = 0; _i < 2; ++_i) \
;         __builtin_amdgcn_global_load_lds((const unsigned*)((const char*)(gbase) + (voff)[_i]), (PG8_LAS unsigned*)(lds + (bufoff) + ldsw + _i * 8192), 16, 0, 0); } while (0)
; #define PG8_LDA(dst, b, h) do { _Pragma("unroll") for (int m = 0; m < 4; ++m) _Pragma("unroll") for (int k = 0; k < 2; ++k) dst[m][k] = *(const PG8_LAS bf16x8*)(lds + PG8_SA(b, h) + aoff + m * 2048 + k * 1024); } while (0)
; #define PG8_MMA(ai, bj, At, Bt) do { __builtin_amdgcn_s_setprio(1); _Pragma("unroll") for (int m = 0; m < 4; ++m) _Pragma("unroll") for (int n = 0; n < 2; ++n) _Pragma("unroll") for (int k = 0; k < 2; ++k) \
;         acc[ai][bj][m][n] = __builtin_amdgcn_mfma_f32_16x16x32_bf16(Bt[n][k], At[m][k], acc[ai][bj][m][n], 0, 0, 0); __builtin_amdgcn_s_setprio(0); } while (0)
; #define PG8_WAIT_V(n) asm volatile("s_waitcnt vmcnt(" #n ")" ::: "memory")
; #define PG8_WAIT_L(n) asm volatile("s_waitcnt lgkmcnt(" #n ")" ::: "memory")
; #define PG8_BAR __builtin_amdgcn_s_barrier()
; #define PG8_SCHED __builtin_amdgcn_sched_barrier(0)
; template <class Epi, class Sched, bool ALIGN_EPI = false, bool SP2 = false>
; __device__ __forceinline__ void gemm_phase(PG8_LAS unsigned char* lds, const Gemm g, const Sched& S, const Epi& E) {
;     ...
;             PG8_WAIT_V(8); PG8_WAIT_L(0); PG8_BAR; PG8_MMA(0, 0, At, B0); PG8_MMA(0, 1, At, B1); PG8_BAR; PG8_SCHED;
;             PG8_LDA(At, 1, 1); PG8_STAGE(PG8_SB(1, 0), b3, voffB); PG8_STAGE(PG8_SB(1, 1), b3 + hstep, voffB); PG8_STAGE(PG8_SA(1, 0), a3, voffA);
;             PG8_WAIT_V(8); PG8_WAIT_L(0); PG8_BAR; PG8_MMA(1, 0, At, B0); PG8_MMA(1, 1, At, B1); PG8_BAR; PG8_SCHED;
	v_mfma_f32_16x16x32_bf16 v[108:111], v[178:181], v[216:219], v[108:111]
	v_mfma_f32_16x16x32_bf16 v[104:107], v[186:189], v[216:219], v[104:107]
	v_mfma_f32_16x16x32_bf16 v[92:95], v[178:181], v[224:227], v[92:95]
	v_mfma_f32_16x16x32_bf16 v[88:91], v[186:189], v[224:227], v[88:91]
	v_mfma_f32_16x16x32_bf16 v[76:79], v[178:181], v[232:235], v[76:79]
	v_mfma_f32_16x16x32_bf16 v[72:75], v[186:189], v[232:235], v[72:75]
	s_setprio 0
	s_add_i32 s16, s18, s41
	v_lshl_add_u64 v[198:199], v[198:199], 0, s[20:21]
	s_mov_b32 m0, s16
	ds_read_b128 v[190:193], v210 offset:49152
	ds_read_b128 v[194:197], v210 offset:50176
	ds_read_b128 v[212:215], v210 offset:51200
	ds_read_b128 v[216:219], v210 offset:52224
	ds_read_b128 v[220:223], v210 offset:53248
	ds_read_b128 v[224:227], v210 offset:54272
	ds_read_b128 v[228:231], v210 offset:55296
	ds_read_b128 v[232:235], v210 offset:56320
	global_load_lds_dwordx4 v[198:199], off
	v_lshl_add_u64 v[198:199], v[236:237], 0, s[20:21]
	s_add_i32 m0, s16, 0x2000
	s_add_i32 s16, s33, s41
	global_load_lds_dwordx4 v[198:199], off
	v_lshl_add_u64 v[198:199], v[238:239], 0, s[20:21]
	s_mov_b32 m0, s16
	s_nop 0
	global_load_lds_dwordx4 v[198:199], off
	v_lshl_add_u64 v[198:199], v[240:241], 0, s[20:21]
	s_add_i32 m0, s16, 0x2000
	s_nop 0
	global_load_lds_dwordx4 v[198:199], off
	v_lshl_add_u64 v[198:199], v[242:243], 0, s[20:21]
	v_lshl_add_u64 v[244:245], v[244:245], 0, s[20:21]
	s_waitcnt vmcnt(6)
	s_waitcnt lgkmcnt(0)
	s_barrier
	s_waitcnt lgkmcnt(0)
	v_mfma_f32_16x16x32_bf16 v[68:71], v[144:147], v[190:193], v[68:71]
	v_mfma_f32_16x16x32_bf16 v[64:67], v[152:155], v[190:193], v[64:67]
	v_mfma_f32_16x16x32_bf16 v[52:55], v[144:147], v[212:215], v[52:55]
	s_mov_b32 m0, s56
	v_mfma_f32_16x16x32_bf16 v[48:51], v[152:155], v[212:215], v[48:51]
	global_load_lds_dwordx4 v[198:199], off
	v_mfma_f32_16x16x32_bf16 v[36:39], v[144:147], v[220:223], v[36:39]
	v_mfma_f32_16x16x32_bf16 v[32:35], v[152:155], v[220:223], v[32:35]
	s_setprio 1
	v_mfma_f32_16x16x32_bf16 v[20:23], v[144:147], v[228:231], v[20:23]
	v_mfma_f32_16x16x32_bf16 v[16:19], v[152:155], v[228:231], v[16:19]
	v_mfma_f32_16x16x32_bf16 v[68:71], v[148:151], v[194:197], v[68:71]
	v_mfma_f32_16x16x32_bf16 v[64:67], v[156:159], v[194:197], v[64:67]
	v_mfma_f32_16x16x32_bf16 v[52:55], v[148:151], v[216:219], v[52:55]
	s_mov_b32 m0, s57
	v_mfma_f32_16x16x32_bf16 v[48:51], v[156:159], v[216:219], v[48:51]
	global_load_lds_dwordx4 v[244:245], off
	v_mfma_f32_16x16x32_bf16 v[36:39], v[148:151], v[224:227], v[36:39]
	v_mfma_f32_16x16x32_bf16 v[32:35], v[156:159], v[224:227], v[32:35]
	v_mfma_f32_16x16x32_bf16 v[20:23], v[148:151], v[232:235], v[20:23]
	v_mfma_f32_16x16x32_bf16 v[16:19], v[156:159], v[232:235], v[16:19]
	s_setprio 0
	s_setprio 1
	v_mfma_f32_16x16x32_bf16 v[60:63], v[160:163], v[190:193], v[60:63]
	v_mfma_f32_16x16x32_bf16 v[56:59], v[182:185], v[190:193], v[56:59]
	v_mfma_f32_16x16x32_bf16 v[44:47], v[160:163], v[212:215], v[44:47]
	v_mfma_f32_16x16x32_bf16 v[40:43], v[182:185], v[212:215], v[40:43]
	v_mfma_f32_16x16x32_bf16 v[28:31], v[160:163], v[220:223], v[28:31]
	v_mfma_f32_16x16x32_bf16 v[24:27], v[182:185], v[220:223], v[24:27]
	v_mfma_f32_16x16x32_bf16 v[12:15], v[160:163], v[228:231], v[12:15]
	v_mfma_f32_16x16x32_bf16 v[8:11], v[182:185], v[228:231], v[8:11]
	v_mfma_f32_16x16x32_bf16 v[60:63], v[178:181], v[194:197], v[60:63]
	v_mfma_f32_16x16x32_bf16 v[56:59], v[186:189], v[194:197], v[56:59]
	s_barrier
	v_mfma_f32_16x16x32_bf16 v[44:47], v[178:181], v[216:219], v[44:47]
	v_mfma_f32_16x16x32_bf16 v[40:43], v[186:189], v[216:219], v[40:43]
	v_mfma_f32_16x16x32_bf16 v[28:31], v[178:181], v[224:227], v[28:31]
	v_mfma_f32_16x16x32_bf16 v[24:27], v[186:189], v[224:227], v[24:27]
	v_mfma_f32_16x16x32_bf16 v[12:15], v[178:181], v[232:235], v[12:15]
	v_mfma_f32_16x16x32_bf16 v[8:11], v[186:189], v[232:235], v[8:11]
	s_setprio 0
	s_add_u32 s24, s24, 0x100
	s_addc_u32 s25, s25, 0
	s_add_u32 s23, s23, 0x100
	s_addc_u32 s35, s35, 0
	s_cmp_ge_u32 s36, s59
	s_mov_b32 s28, s36
	s_cbranch_scc0 .LBB0_203
	s_and_b64 vcc, exec, s[46:47]
	s_cbranch_vccz .LBB0_206
	s_barrier
	s_setprio 1

; #define PG8_STAGE(bufoff, gbase, voff) do { _Pragma("unroll") for (int _i = 0; _i < 2; ++_i) \
;         __builtin_amdgcn_global_load_lds((const unsigned*)((const char*)(gbase) + (voff)[_i]), (PG8_LAS unsigned*)(lds + (bufoff) + ldsw + _i * 8192), 16, 0, 0); } while (0)
; #define PG8_LDA(dst, b, h) do { _Pragma("unroll") for (int m = 0; m < 4; ++m) _Pragma("unroll") for (int k = 0; k < 2; ++k) dst[m][k] = *(const PG8_LAS bf16x8*)(lds + PG8_SA(b, h) + aoff + m * 2048 + k * 1024); } while (0)
; #define PG8_LDB(dst, b, h) do { _Pragma("unroll") for (int n = 0; n < 2; ++n) _Pragma("unroll") for (int k = 0; k < 2; ++k) dst[n][k] = *(const PG8_LAS bf16x8*)(lds + PG8_SB(b, h) + boff + n * 2048 + k * 1024); } while (0)
; #define PG8_MMA(ai, bj, At, Bt) do { __builtin_amdgcn_s_setprio(1); _Pragma("unroll") for (int m = 0; m < 4; ++m) _Pragma("unroll") for (int n = 0; n < 2; ++n) _Pragma("unroll") for (int k = 0; k < 2; ++k) \
;         acc[ai][bj][m][n] = __builtin_amdgcn_mfma_f32_16x16x32_bf16(Bt[n][k], At[m][k], acc[ai][bj][m][n], 0, 0, 0); __builtin_amdgcn_s_setprio(0); } while (0)
; #define PG8_WAIT_V(n) asm volatile("s_waitcnt vmcnt(" #n ")" ::: "memory")
; #define PG8_BAR __builtin_amdgcn_s_barrier()
; template <class Epi, class Sched, bool ALIGN_EPI = false, bool SP2 = false>
; __device__ __forceinline__ void gemm_phase(PG8_LAS unsigned char* lds, const Gemm g, const Sched& S, const Epi& E) {
;     ...
;         for (int t = 0; t < nt; t += 2) {
;             const bool last = (t == nt - 2);
;             const char* a1 = cA + (size_t)(t + 1) * kstep;
;             const char* a2 = last ? nA : cA + (size_t)(t + 2) * kstep; const char* b2 = last ? nB : cB + (size_t)(t + 2) * kstep;
;             const char* a3 = a2 + kstep; const char* b3 = b2 + kstep;
;             if (last && has_next) S.a_ready(nxt);
;             if constexpr (SP2) {
;             PG8_LDB(B0, 0, 0); PG8_LDB(B1, 0, 1); PG8_SCHED; PG8_LDA(At, 0, 0); PG8_STAGE(PG8_SA(1, 1), a1 + hstep, voffA);
;             PG8_WAIT_V(8); PG8_WAIT_L(0); PG8_BAR; PG8_MMA(0, 0, At, B0); PG8_MMA(0, 1, At, B1); PG8_BAR; PG8_SCHED;
;             PG8_LDA(At, 0, 1); PG8_STAGE(PG8_SB(0, 0), b2, voffB); PG8_STAGE(PG8_SB(0, 1), b2 + hstep, voffB); PG8_STAGE(PG8_SA(0, 0), a2, voffA);
;             PG8_WAIT_V(8); PG8_WAIT_L(0); PG8_BAR; PG8_MMA(1, 0, At, B0); PG8_MMA(1, 1, At, B1); PG8_BAR; PG8_SCHED;
.LBB0_257:
	s_add_u32 s16, s8, 0xfffc0080
	s_addc_u32 s17, s9, -1
	s_add_i32 s18, 0, 0x10000
	s_cmp_eq_u32 s55, 12
	s_cselect_b32 s43, s14, s17
	s_cselect_b32 s42, s15, s16
	v_add_u32_e32 v0, s18, v210
	s_cselect_b32 s41, s13, s54
	s_cselect_b32 s40, s25, s53
	s_add_i32 s19, 0, 0x14000
	ds_read_b128 v[104:107], v0
	ds_read_b128 v[140:143], v0 offset:1024
	ds_read_b128 v[144:147], v0 offset:2048
	ds_read_b128 v[148:151], v0 offset:3072
	v_add_u32_e32 v0, s19, v210
	ds_read_b128 v[152:155], v0
	ds_read_b128 v[156:159], v0 offset:1024
	ds_read_b128 v[160:163], v0 offset:2048
	ds_read_b128 v[192:195], v0 offset:3072
	v_lshl_add_u64 v[2:3], s[8:9], 0, v[188:189]
	s_add_i32 m0, s44, 0xc000
	ds_read_b128 v[196:199], v212
	ds_read_b128 v[214:217], v212 offset:1024
	ds_read_b128 v[218:221], v212 offset:2048
	ds_read_b128 v[222:225], v212 offset:3072
	ds_read_b128 v[226:229], v212 offset:4096
	ds_read_b128 v[230:233], v212 offset:5120
	ds_read_b128 v[234:237], v212 offset:6144
	ds_read_b128 v[238:241], v212 offset:7168
	global_load_lds_dwordx4 v[2:3], off
	v_lshl_add_u64 v[2:3], s[8:9], 0, v[190:191]
	s_add_i32 m0, s44, 0xe000
	s_nop 0
	global_load_lds_dwordx4 v[2:3], off
	s_waitcnt vmcnt(8)
	s_waitcnt lgkmcnt(0)
	s_barrier
	s_waitcnt lgkmcnt(0)
	v_mfma_f32_16x16x32_bf16 v[136:139], v[104:107], v[196:199], v[136:139]
	v_mfma_f32_16x16x32_bf16 v[128:131], v[144:147], v[196:199], v[128:131]
	v_mfma_f32_16x16x32_bf16 v[120:123], v[104:107], v[218:221], v[120:123]
	v_mfma_f32_16x16x32_bf16 v[112:115], v[144:147], v[218:221], v[112:115]
	v_mfma_f32_16x16x32_bf16 v[100:103], v[104:107], v[226:229], v[100:103]
	v_mfma_f32_16x16x32_bf16 v[92:95], v[144:147], v[226:229], v[92:95]
	s_setprio 1
	v_mfma_f32_16x16x32_bf16 v[84:87], v[104:107], v[234:237], v[84:87]
	v_mfma_f32_16x16x32_bf16 v[76:79], v[144:147], v[234:237], v[76:79]
	v_mfma_f32_16x16x32_bf16 v[136:139], v[140:143], v[214:217], v[136:139]
	v_mfma_f32_16x16x32_bf16 v[128:131], v[148:151], v[214:217], v[128:131]
	v_mfma_f32_16x16x32_bf16 v[120:123], v[140:143], v[222:225], v[120:123]
	v_mfma_f32_16x16x32_bf16 v[112:115], v[148:151], v[222:225], v[112:115]
	v_mfma_f32_16x16x32_bf16 v[100:103], v[140:143], v[230:233], v[100:103]
	v_mfma_f32_16x16x32_bf16 v[92:95], v[148:151], v[230:233], v[92:95]
	v_mfma_f32_16x16x32_bf16 v[84:87], v[140:143], v[238:241], v[84:87]
	v_mfma_f32_16x16x32_bf16 v[76:79], v[148:151], v[238:241], v[76:79]
	s_setprio 0
	s_setprio 1
	v_mfma_f32_16x16x32_bf16 v[132:135], v[152:155], v[196:199], v[132:135]
	v_mfma_f32_16x16x32_bf16 v[124:127], v[160:163], v[196:199], v[124:127]
	v_mfma_f32_16x16x32_bf16 v[116:119], v[152:155], v[218:221], v[116:119]
	v_mfma_f32_16x16x32_bf16 v[108:111], v[160:163], v[218:221], v[108:111]
	v_mfma_f32_16x16x32_bf16 v[96:99], v[152:155], v[226:229], v[96:99]
	v_mfma_f32_16x16x32_bf16 v[88:91], v[160:163], v[226:229], v[88:91]
	v_mfma_f32_16x16x32_bf16 v[80:83], v[152:155], v[234:237], v[80:83]
	v_mfma_f32_16x16x32_bf16 v[72:75], v[160:163], v[234:237], v[72:75]
	v_mfma_f32_16x16x32_bf16 v[132:135], v[156:159], v[214:217], v[132:135]
	v_mfma_f32_16x16x32_bf16 v[124:127], v[192:195], v[214:217], v[124:127]
	s_barrier
	v_mfma_f32_16x16x32_bf16 v[116:119], v[156:159], v[222:225], v[116:119]
	v_mfma_f32_16x16x32_bf16 v[108:111], v[192:195], v[222:225], v[108:111]
	v_mfma_f32_16x16x32_bf16 v[96:99], v[156:159], v[230:233], v[96:99]
	v_mfma_f32_16x16x32_bf16 v[88:91], v[192:195], v[230:233], v[88:91]
	v_mfma_f32_16x16x32_bf16 v[80:83], v[156:159], v[238:241], v[80:83]
	v_mfma_f32_16x16x32_bf16 v[72:75], v[192:195], v[238:241], v[72:75]
	s_setprio 0
	s_add_i32 s16, s18, s36
	v_lshl_add_u64 v[2:3], s[40:41], 0, v[182:183]
	s_mov_b32 m0, s16
	ds_read_b128 v[196:199], v212 offset:16384
	ds_read_b128 v[214:217], v212 offset:17408
	ds_read_b128 v[218:221], v212 offset:18432
	ds_read_b128 v[222:225], v212 offset:19456
	ds_read_b128 v[226:229], v212 offset:20480
	ds_read_b128 v[230:233], v212 offset:21504
	ds_read_b128 v[234:237], v212 offset:22528
	ds_read_b128 v[238:241], v212 offset:23552
	global_load_lds_dwordx4 v[2:3], off
	s_add_i32 m0, s16, 0x2000
	s_add_u32 s16, s40, 0x40000
	v_lshl_add_u64 v[200:201], s[40:41], 0, v[178:179]
	s_addc_u32 s17, s41, 0
	s_add_i32 s18, s19, s36
	global_load_lds_dwordx4 v[200:201], off
	v_lshl_add_u64 v[242:243], s[16:17], 0, v[182:183]
	s_mov_b32 m0, s18
	v_lshl_add_u64 v[244:245], s[42:43], 0, v[180:181]
	global_load_lds_dwordx4 v[242:243], off
	v_lshl_add_u64 v[242:243], s[16:17], 0, v[178:179]
	s_add_i32 m0, s18, 0x2000
	s_nop 0
	global_load_lds_dwordx4 v[242:243], off
	v_lshl_add_u64 v[242:243], s[42:43], 0, v[184:185]
	s_waitcnt vmcnt(6)
	s_waitcnt lgkmcnt(0)
	s_barrier
; #define PG8_STAGE(bufoff, gbase, voff) do { _Pragma("unroll") for (int _i = 0; _i < 2; ++_i) \
;         __builtin_amdgcn_global_load_lds((const unsigned*)((const char*)(gbase) + (voff)[_i]), (PG8_LAS unsigned*)(lds + (bufoff) + ldsw + _i * 8192), 16, 0, 0); } while (0)
; #define PG8_LDA(dst, b, h) do { _Pragma("unroll") for (int m = 0; m < 4; ++m) _Pragma("unroll") for (int k = 0; k < 2; ++k) dst[m][k] = *(const PG8_LAS bf16x8*)(lds + PG8_SA(b, h) + aoff + m * 2048 + k * 1024); } while (0)
; #define PG8_LDB(dst, b, h) do { _Pragma("unroll") for (int n = 0; n < 2; ++n) _Pragma("unroll") for (int k = 0; k < 2; ++k) dst[n][k] = *(const PG8_LAS bf16x8*)(lds + PG8_SB(b, h) + boff + n * 2048 + k * 1024); } while (0)
; #define PG8_MMA(ai, bj, At, Bt) do { __builtin_amdgcn_s_setprio(1); _Pragma("unroll") for (int m = 0; m < 4; ++m) _Pragma("unroll") for (int n = 0; n < 2; ++n) _Pragma("unroll") for (int k = 0; k < 2; ++k) \
;         acc[ai][bj][m][n] = __builtin_amdgcn_mfma_f32_16x16x32_bf16(Bt[n][k], At[m][k], acc[ai][bj][m][n], 0, 0, 0); __builtin_amdgcn_s_setprio(0); } while (0)
; #define PG8_WAIT_V(n) asm volatile("s_waitcnt vmcnt(" #n ")" ::: "memory")
; #define PG8_WAIT_L(n) asm volatile("s_waitcnt lgkmcnt(" #n ")" ::: "memory")
; #define PG8_BAR __builtin_amdgcn_s_barrier()
; #define PG8_SCHED __builtin_amdgcn_sched_barrier(0)
; template <class Epi, class Sched, bool ALIGN_EPI = false, bool SP2 = false>
; __device__ __forceinline__ void gemm_phase(PG8_LAS unsigned char* lds, const Gemm g, const Sched& S, const Epi& E) {
;     ...
;             PG8_WAIT_V(8); PG8_WAIT_L(0); PG8_BAR; PG8_MMA(1, 0, At, B0); PG8_MMA(1, 1, At, B1); PG8_BAR; PG8_SCHED;
;             PG8_LDB(B0, 1, 0); PG8_LDB(B1, 1, 1); PG8_SCHED; PG8_LDA(At, 1, 0); PG8_STAGE(PG8_SA(0, 1), a2 + hstep, voffA);
;             PG8_WAIT_V(8); PG8_WAIT_L(0); PG8_BAR; PG8_MMA(0, 0, At, B0); PG8_MMA(0, 1, At, B1); PG8_BAR; PG8_SCHED;
	s_waitcnt lgkmcnt(0)
	v_mfma_f32_16x16x32_bf16 v[68:71], v[104:107], v[196:199], v[68:71]
	v_mfma_f32_16x16x32_bf16 v[60:63], v[144:147], v[196:199], v[60:63]
	v_mfma_f32_16x16x32_bf16 v[52:55], v[104:107], v[218:221], v[52:55]
	s_mov_b32 m0, s44
	v_mfma_f32_16x16x32_bf16 v[44:47], v[144:147], v[218:221], v[44:47]
	global_load_lds_dwordx4 v[242:243], off
	v_mfma_f32_16x16x32_bf16 v[36:39], v[104:107], v[226:229], v[36:39]
	v_mfma_f32_16x16x32_bf16 v[28:31], v[144:147], v[226:229], v[28:31]
	s_setprio 1
	v_mfma_f32_16x16x32_bf16 v[20:23], v[104:107], v[234:237], v[20:23]
	v_mfma_f32_16x16x32_bf16 v[12:15], v[144:147], v[234:237], v[12:15]
	v_mfma_f32_16x16x32_bf16 v[68:71], v[140:143], v[214:217], v[68:71]
	v_mfma_f32_16x16x32_bf16 v[60:63], v[148:151], v[214:217], v[60:63]
	v_mfma_f32_16x16x32_bf16 v[52:55], v[140:143], v[222:225], v[52:55]
	s_mov_b32 m0, s45
	v_mfma_f32_16x16x32_bf16 v[44:47], v[148:151], v[222:225], v[44:47]
	global_load_lds_dwordx4 v[244:245], off
	v_mfma_f32_16x16x32_bf16 v[36:39], v[140:143], v[230:233], v[36:39]
	v_mfma_f32_16x16x32_bf16 v[28:31], v[148:151], v[230:233], v[28:31]
	v_mfma_f32_16x16x32_bf16 v[20:23], v[140:143], v[238:241], v[20:23]
	v_mfma_f32_16x16x32_bf16 v[12:15], v[148:151], v[238:241], v[12:15]
	s_setprio 0
	s_setprio 1
	v_mfma_f32_16x16x32_bf16 v[64:67], v[152:155], v[196:199], v[64:67]
	v_mfma_f32_16x16x32_bf16 v[56:59], v[160:163], v[196:199], v[56:59]
	v_mfma_f32_16x16x32_bf16 v[48:51], v[152:155], v[218:221], v[48:51]
	v_mfma_f32_16x16x32_bf16 v[40:43], v[160:163], v[218:221], v[40:43]
	v_mfma_f32_16x16x32_bf16 v[32:35], v[152:155], v[226:229], v[32:35]
	v_mfma_f32_16x16x32_bf16 v[24:27], v[160:163], v[226:229], v[24:27]
	v_mfma_f32_16x16x32_bf16 v[16:19], v[152:155], v[234:237], v[16:19]
	v_mfma_f32_16x16x32_bf16 v[8:11], v[160:163], v[234:237], v[8:11]
	v_mfma_f32_16x16x32_bf16 v[64:67], v[156:159], v[214:217], v[64:67]
	v_mfma_f32_16x16x32_bf16 v[56:59], v[192:195], v[214:217], v[56:59]
	s_barrier
	v_mfma_f32_16x16x32_bf16 v[48:51], v[156:159], v[222:225], v[48:51]
	v_mfma_f32_16x16x32_bf16 v[40:43], v[192:195], v[222:225], v[40:43]
	v_mfma_f32_16x16x32_bf16 v[32:35], v[156:159], v[230:233], v[32:35]
	v_mfma_f32_16x16x32_bf16 v[24:27], v[192:195], v[230:233], v[24:27]
	v_mfma_f32_16x16x32_bf16 v[16:19], v[156:159], v[238:241], v[16:19]
	v_mfma_f32_16x16x32_bf16 v[8:11], v[192:195], v[238:241], v[8:11]
	s_setprio 0
	s_add_i32 s18, 0, 0x18000
	v_add_u32_e32 v0, s18, v210
	ds_read_b128 v[104:107], v0
	ds_read_b128 v[140:143], v0 offset:1024
	ds_read_b128 v[144:147], v0 offset:2048
	ds_read_b128 v[148:151], v0 offset:3072
	v_add_u32_e32 v0, s33, v210
	ds_read_b128 v[152:155], v0
	ds_read_b128 v[156:159], v0 offset:1024
	ds_read_b128 v[160:163], v0 offset:2048
	ds_read_b128 v[192:195], v0 offset:3072
	s_add_u32 s16, s42, 0x40000
	s_addc_u32 s17, s43, 0
	s_mov_b32 m0, s46
	v_lshl_add_u64 v[246:247], s[16:17], 0, v[184:185]
	ds_read_b128 v[196:199], v212 offset:32768
	ds_read_b128 v[214:217], v212 offset:33792
	ds_read_b128 v[218:221], v212 offset:34816
	ds_read_b128 v[222:225], v212 offset:35840
	ds_read_b128 v[226:229], v212 offset:36864
	ds_read_b128 v[230:233], v212 offset:37888
	ds_read_b128 v[234:237], v212 offset:38912
	ds_read_b128 v[238:241], v212 offset:39936
	global_load_lds_dwordx4 v[246:247], off
	v_lshl_add_u64 v[246:247], s[16:17], 0, v[180:181]
	s_mov_b32 m0, s47
	s_nop 0
	global_load_lds_dwordx4 v[246:247], off
	s_waitcnt vmcnt(8)
	s_waitcnt lgkmcnt(0)
	s_barrier
	s_waitcnt lgkmcnt(0)
	v_mfma_f32_16x16x32_bf16 v[136:139], v[104:107], v[196:199], v[136:139]
	v_mfma_f32_16x16x32_bf16 v[128:131], v[144:147], v[196:199], v[128:131]
	v_mfma_f32_16x16x32_bf16 v[120:123], v[104:107], v[218:221], v[120:123]
	v_mfma_f32_16x16x32_bf16 v[112:115], v[144:147], v[218:221], v[112:115]
	v_mfma_f32_16x16x32_bf16 v[100:103], v[104:107], v[226:229], v[100:103]
	v_mfma_f32_16x16x32_bf16 v[92:95], v[144:147], v[226:229], v[92:95]
	s_setprio 1
	v_mfma_f32_16x16x32_bf16 v[84:87], v[104:107], v[234:237], v[84:87]
	v_mfma_f32_16x16x32_bf16 v[76:79], v[144:147], v[234:237], v[76:79]
	v_mfma_f32_16x16x32_bf16 v[136:139], v[140:143], v[214:217], v[136:139]
	v_mfma_f32_16x16x32_bf16 v[128:131], v[148:151], v[214:217], v[128:131]
	v_mfma_f32_16x16x32_bf16 v[120:123], v[140:143], v[222:225], v[120:123]
	v_mfma_f32_16x16x32_bf16 v[112:115], v[148:151], v[222:225], v[112:115]
	v_mfma_f32_16x16x32_bf16 v[100:103], v[140:143], v[230:233], v[100:103]
	v_mfma_f32_16x16x32_bf16 v[92:95], v[148:151], v[230:233], v[92:95]
	v_mfma_f32_16x16x32_bf16 v[84:87], v[140:143], v[238:241], v[84:87]
	v_mfma_f32_16x16x32_bf16 v[76:79], v[148:151], v[238:241], v[76:79]
	s_setprio 0
	s_setprio 1
	v_mfma_f32_16x16x32_bf16 v[132:135], v[152:155], v[196:199], v[132:135]
	v_mfma_f32_16x16x32_bf16 v[124:127], v[160:163], v[196:199], v[124:127]
	v_mfma_f32_16x16x32_bf16 v[116:119], v[152:155], v[218:221], v[116:119]
	v_mfma_f32_16x16x32_bf16 v[108:111], v[160:163], v[218:221], v[108:111]
	v_mfma_f32_16x16x32_bf16 v[96:99], v[152:155], v[226:229], v[96:99]
	v_mfma_f32_16x16x32_bf16 v[88:91], v[160:163], v[226:229], v[88:91]
	v_mfma_f32_16x16x32_bf16 v[80:83], v[152:155], v[234:237], v[80:83]
	v_mfma_f32_16x16x32_bf16 v[72:75], v[160:163], v[234:237], v[72:75]
	v_mfma_f32_16x16x32_bf16 v[132:135], v[156:159], v[214:217], v[132:135]
	v_mfma_f32_16x16x32_bf16 v[124:127], v[192:195], v[214:217], v[124:127]
	s_barrier
; #define PG8_STAGE(bufoff, gbase, voff) do { _Pragma("unroll") for (int _i = 0; _i < 2; ++_i) \
;         __builtin_amdgcn_global_load_lds((const unsigned*)((const char*)(gbase) + (voff)[_i]), (PG8_LAS unsigned*)(lds + (bufoff) + ldsw + _i * 8192), 16, 0, 0); } while (0)
; #define PG8_LDA(dst, b, h) do { _Pragma("unroll") for (int m = 0; m < 4; ++m) _Pragma("unroll") for (int k = 0; k < 2; ++k) dst[m][k] = *(const PG8_LAS bf16x8*)(lds + PG8_SA(b, h) + aoff + m * 2048 + k * 1024); } while (0)
; #define PG8_MMA(ai, bj, At, Bt) do { __builtin_amdgcn_s_setprio(1); _Pragma("unroll") for (int m = 0; m < 4; ++m) _Pragma("unroll") for (int n = 0; n < 2; ++n) _Pragma("unroll") for (int k = 0; k < 2; ++k) \
;         acc[ai][bj][m][n] = __builtin_amdgcn_mfma_f32_16x16x32_bf16(Bt[n][k], At[m][k], acc[ai][bj][m][n], 0, 0, 0); __builtin_amdgcn_s_setprio(0); } while (0)
; #define PG8_WAIT_V(n) asm volatile("s_waitcnt vmcnt(" #n ")" ::: "memory")
; #define PG8_WAIT_L(n) asm volatile("s_waitcnt lgkmcnt(" #n ")" ::: "memory")
; #define PG8_BAR __builtin_amdgcn_s_barrier()
; #define PG8_SCHED __builtin_amdgcn_sched_barrier(0)
; template <class Epi, class Sched, bool ALIGN_EPI = false, bool SP2 = false>
; __device__ __forceinline__ void gemm_phase(PG8_LAS unsigned char* lds, const Gemm g, const Sched& S, const Epi& E) {
;     ...
;             PG8_WAIT_V(8); PG8_WAIT_L(0); PG8_BAR; PG8_MMA(0, 0, At, B0); PG8_MMA(0, 1, At, B1); PG8_BAR; PG8_SCHED;
;             PG8_LDA(At, 1, 1); PG8_STAGE(PG8_SB(1, 0), b3, voffB); PG8_STAGE(PG8_SB(1, 1), b3 + hstep, voffB); PG8_STAGE(PG8_SA(1, 0), a3, voffA);
;             PG8_WAIT_V(8); PG8_WAIT_L(0); PG8_BAR; PG8_MMA(1, 0, At, B0); PG8_MMA(1, 1, At, B1); PG8_BAR; PG8_SCHED;
	v_mfma_f32_16x16x32_bf16 v[116:119], v[156:159], v[222:225], v[116:119]
	v_mfma_f32_16x16x32_bf16 v[108:111], v[192:195], v[222:225], v[108:111]
	v_mfma_f32_16x16x32_bf16 v[96:99], v[156:159], v[230:233], v[96:99]
	v_mfma_f32_16x16x32_bf16 v[88:91], v[192:195], v[230:233], v[88:91]
	v_mfma_f32_16x16x32_bf16 v[80:83], v[156:159], v[238:241], v[80:83]
	v_mfma_f32_16x16x32_bf16 v[72:75], v[192:195], v[238:241], v[72:75]
	s_setprio 0
	s_add_i32 s16, s18, s36
	v_lshl_add_u64 v[2:3], v[2:3], 0, s[20:21]
	s_mov_b32 m0, s16
	ds_read_b128 v[196:199], v212 offset:49152
	ds_read_b128 v[214:217], v212 offset:50176
	ds_read_b128 v[218:221], v212 offset:51200
	ds_read_b128 v[222:225], v212 offset:52224
	ds_read_b128 v[226:229], v212 offset:53248
	ds_read_b128 v[230:233], v212 offset:54272
	ds_read_b128 v[234:237], v212 offset:55296
	ds_read_b128 v[238:241], v212 offset:56320
	global_load_lds_dwordx4 v[2:3], off
	s_add_i32 m0, s16, 0x2000
	s_add_u32 s16, s40, 0x40080
	v_lshl_add_u64 v[2:3], v[200:201], 0, s[20:21]
	s_addc_u32 s17, s41, 0
	s_add_i32 s18, s33, s36
	global_load_lds_dwordx4 v[2:3], off
	v_lshl_add_u64 v[2:3], s[16:17], 0, v[182:183]
	s_mov_b32 m0, s18
	s_nop 0
	global_load_lds_dwordx4 v[2:3], off
	v_lshl_add_u64 v[2:3], s[16:17], 0, v[178:179]
	s_add_i32 m0, s18, 0x2000
	s_nop 0
	global_load_lds_dwordx4 v[2:3], off
	v_lshl_add_u64 v[2:3], v[242:243], 0, s[20:21]
	v_lshl_add_u64 v[244:245], v[244:245], 0, s[20:21]
	s_waitcnt vmcnt(6)
	s_waitcnt lgkmcnt(0)
	s_barrier
	s_waitcnt lgkmcnt(0)
	v_mfma_f32_16x16x32_bf16 v[68:71], v[104:107], v[196:199], v[68:71]
	v_mfma_f32_16x16x32_bf16 v[60:63], v[144:147], v[196:199], v[60:63]
	v_mfma_f32_16x16x32_bf16 v[52:55], v[104:107], v[218:221], v[52:55]
	s_mov_b32 m0, s48
	v_mfma_f32_16x16x32_bf16 v[44:47], v[144:147], v[218:221], v[44:47]
	global_load_lds_dwordx4 v[2:3], off
	v_mfma_f32_16x16x32_bf16 v[36:39], v[104:107], v[226:229], v[36:39]
	v_mfma_f32_16x16x32_bf16 v[28:31], v[144:147], v[226:229], v[28:31]
	s_setprio 1
	v_mfma_f32_16x16x32_bf16 v[20:23], v[104:107], v[234:237], v[20:23]
	v_mfma_f32_16x16x32_bf16 v[12:15], v[144:147], v[234:237], v[12:15]
	v_mfma_f32_16x16x32_bf16 v[68:71], v[140:143], v[214:217], v[68:71]
	v_mfma_f32_16x16x32_bf16 v[60:63], v[148:151], v[214:217], v[60:63]
	v_mfma_f32_16x16x32_bf16 v[52:55], v[140:143], v[222:225], v[52:55]
	s_mov_b32 m0, s49
	v_mfma_f32_16x16x32_bf16 v[44:47], v[148:151], v[222:225], v[44:47]
	global_load_lds_dwordx4 v[244:245], off
	v_mfma_f32_16x16x32_bf16 v[36:39], v[140:143], v[230:233], v[36:39]
	v_mfma_f32_16x16x32_bf16 v[28:31], v[148:151], v[230:233], v[28:31]
	v_mfma_f32_16x16x32_bf16 v[20:23], v[140:143], v[238:241], v[20:23]
	v_mfma_f32_16x16x32_bf16 v[12:15], v[148:151], v[238:241], v[12:15]
	s_setprio 0
	s_setprio 1
	v_mfma_f32_16x16x32_bf16 v[64:67], v[152:155], v[196:199], v[64:67]
	v_mfma_f32_16x16x32_bf16 v[56:59], v[160:163], v[196:199], v[56:59]
	v_mfma_f32_16x16x32_bf16 v[48:51], v[152:155], v[218:221], v[48:51]
	v_mfma_f32_16x16x32_bf16 v[40:43], v[160:163], v[218:221], v[40:43]
	v_mfma_f32_16x16x32_bf16 v[32:35], v[152:155], v[226:229], v[32:35]
	v_mfma_f32_16x16x32_bf16 v[24:27], v[160:163], v[226:229], v[24:27]
	v_mfma_f32_16x16x32_bf16 v[16:19], v[152:155], v[234:237], v[16:19]
	v_mfma_f32_16x16x32_bf16 v[8:11], v[160:163], v[234:237], v[8:11]
	v_mfma_f32_16x16x32_bf16 v[64:67], v[156:159], v[214:217], v[64:67]
	v_mfma_f32_16x16x32_bf16 v[56:59], v[192:195], v[214:217], v[56:59]
	s_barrier
	v_mfma_f32_16x16x32_bf16 v[48:51], v[156:159], v[222:225], v[48:51]
	v_mfma_f32_16x16x32_bf16 v[40:43], v[192:195], v[222:225], v[40:43]
	v_mfma_f32_16x16x32_bf16 v[32:35], v[156:159], v[230:233], v[32:35]
	v_mfma_f32_16x16x32_bf16 v[24:27], v[192:195], v[230:233], v[24:27]
	v_mfma_f32_16x16x32_bf16 v[16:19], v[156:159], v[238:241], v[16:19]
	v_mfma_f32_16x16x32_bf16 v[8:11], v[192:195], v[238:241], v[8:11]
	s_setprio 0
	s_add_i32 s55, s55, 2
	s_add_u32 s8, s8, 0x100
	s_addc_u32 s9, s9, 0
	s_add_u32 s53, s53, 0x100
	s_addc_u32 s54, s54, 0
	s_cmp_gt_u32 s55, 13
	s_cbranch_scc0 .LBB0_257
	s_and_b64 vcc, exec, s[10:11]
	s_cbranch_vccz .LBB0_260
	s_barrier
	s_setprio 1
